# v014 + half-grid start offset (~5us) in the out-proj phase as well
# speedup vs baseline: 1.0120x; 1.0047x over previous
.LBB0_864:
	s_or_b64 exec, exec, s[0:1]
	v_readlane_b32 s0, v247, 4
	s_mul_hi_u32 s0, s0, 0x210
	v_readlane_b32 s3, v247, 5
	s_mul_i32 s0, s0, s3
	s_sub_i32 s0, 0x210, s0
	s_sub_i32 s1, s0, s3
	s_cmp_ge_u32 s0, s3
	s_cselect_b32 s0, s1, s0
	s_sub_i32 s1, s0, s3
	s_cmp_ge_u32 s0, s3
	s_cselect_b32 s33, s1, s0
	s_sub_i32 s3, 0x210, s33
	s_cmp_ge_i32 s2, s3
	v_lshrrev_b32_e32 v70, 3, v184
	v_lshlrev_b32_e32 v71, 2, v184
	s_barrier
	s_cbranch_scc1 .LBB0_873
	v_readlane_b32 s0, v247, 0
	v_readlane_b32 s1, v247, 1
	s_add_u32 s0, s0, 8
	s_addc_u32 s1, s1, 0
	s_add_u32 s38, s54, 0x2b75100
	s_addc_u32 s39, s55, 0
	s_add_u32 s40, s54, 0x975100
	s_addc_u32 s41, s55, 0
	v_and_b32_e32 v0, 4, v70
	v_lshl_or_b32 v75, v209, 10, v188
	s_add_u32 s42, s52, 0x4000000
	v_and_b32_e32 v72, 0x7c, v71
	v_mul_u32_u24_e32 v73, 0x110, v209
	v_mul_u32_u24_e32 v74, 0x110, v0
	v_or_b32_e32 v76, 0x1000, v75
	v_or_b32_e32 v77, 0x2000, v75
	v_or_b32_e32 v78, 0x3000, v75
	v_or_b32_e32 v79, 0x4000, v75
	v_or_b32_e32 v80, 0x5000, v75
	v_or_b32_e32 v81, 0x6000, v75
	v_or_b32_e32 v82, 0x7000, v75
	s_addc_u32 s43, s53, 0
	s_lshl_b32 s44, s2, 8
	s_lshl_b32 s45, s86, 8
	s_mov_b32 s5, 0
	v_mov_b32_e32 v69, 0
	s_mov_b64 s[6:7], 0x20000
	s_mov_b64 s[8:9], 0x40000
	s_mov_b64 s[10:11], 0x60000
	s_mov_b32 s46, 0xa000
	s_mov_b64 s[12:13], 0x2b75180
	s_mov_b64 s[14:15], 0x2b95180
	s_mov_b64 s[16:17], 0x975180
	s_mov_b64 s[18:19], 0x995180
	s_mov_b64 s[20:21], 0x9b5180
	s_mov_b64 s[22:23], 0x9d5180
	s_mov_b32 s47, s2
	s_cmp_lt_u32 s2, 0x80
	s_cbranch_scc1 .LBB0_868
	s_movk_i32 s20, 10
.Lg2_delay:
	s_sleep 16
	s_add_i32 s20, s20, -1
	s_cmp_lg_u32 s20, 0
	s_cbranch_scc1 .Lg2_delay
	s_branch .LBB0_868
